# adds: band prologue bias-table loads issued together with Q/K/V loads
# speedup vs baseline: 1.0127x; 1.0031x over previous
.LBB0_375:
	v_mov_b32_e32 v8, v204
	s_lshl_b32 s0, s40, 1
	s_and_b32 s0, s0, 6
	v_readfirstlane_b32 s15, v8
	s_ashr_i32 s22, s15, 8
	s_add_i32 s23, s22, s0
	s_mul_i32 s0, s22, 0x404
	s_add_i32 s14, s0, 0
	s_add_i32 s0, s23, s2
	s_mulk_i32 s0, 0x101
	s_ashr_i32 s1, s0, 31
	v_readlane_b32 s64, v236, 11
	s_add_i32 s14, s14, 0x23000
	s_lshl_b64 s[0:1], s[0:1], 2
	v_readlane_b32 s70, v236, 17
	v_readlane_b32 s71, v236, 18
	s_add_u32 s0, s70, s0
	s_addc_u32 s1, s71, s1
	v_lshlrev_b32_sdwa v0, v210, v8 dst_sel:DWORD dst_unused:UNUSED_PAD src0_sel:DWORD src1_sel:BYTE_0
	global_load_dword v244, v0, s[0:1]
	v_add_u32_e32 v245, s14, v0
	v_cmp_eq_u32_sdwa s[24:25], v8, v1 src0_sel:BYTE_0 src1_sel:DWORD
	v_readlane_b32 s65, v236, 12
	v_readlane_b32 s66, v236, 13
	v_readlane_b32 s67, v236, 14
	v_readlane_b32 s68, v236, 15
	v_readlane_b32 s69, v236, 16
	v_readlane_b32 s72, v236, 19
	v_readlane_b32 s73, v236, 20
	v_readlane_b32 s74, v236, 21
	v_readlane_b32 s75, v236, 22
	v_readlane_b32 s76, v236, 23
	v_readlane_b32 s77, v236, 24
	v_readlane_b32 s78, v236, 25
	v_readlane_b32 s79, v236, 26
	global_load_dword v246, v1, s[0:1] offset:1024
.LBB0_377:
	s_ashr_i32 s39, s40, 2
	s_bfe_u32 s15, s15, 0x20006
	s_lshl_b32 s0, s23, 7
	s_ashr_i32 s1, s0, 31
	s_mul_i32 s24, s23, 0x204000
	s_lshl_b32 s38, s39, 7
	s_lshl_b32 s23, s15, 5
	s_mul_hi_i32 s25, s0, 0x4080
	s_or_b32 s18, s23, s38
	s_lshl_b64 s[0:1], s[0:1], 1
	v_bfe_u32 v7, v8, 4, 2
	s_add_u32 s36, s4, s0
	v_and_b32_e32 v6, 15, v8
	s_addc_u32 s37, s5, s1
	v_lshlrev_b32_e32 v2, 4, v7
	v_mov_b32_e32 v3, v1
	v_or_b32_e32 v192, s18, v6
	v_lshl_add_u64 v[14:15], s[36:37], 0, v[2:3]
	v_mad_i64_i32 v[4:5], s[18:19], v192, s59, v[14:15]
	s_add_u32 s18, s8, s24
	s_addc_u32 s19, s9, s25
	s_lshl_b32 s24, s39, 1
	s_sub_i32 s25, 8, s24
	s_max_i32 s25, s25, 0
	s_add_i32 s24, s24, s25
	s_lshl_b32 s24, s24, 6
	s_add_i32 s42, s24, 0xfffffe00
	v_lshlrev_b32_e32 v24, 4, v8
	v_and_b32_e32 v16, 0xf0, v24
	v_mov_b32_e32 v17, v1
	s_ashr_i32 s43, s42, 31
	v_lshlrev_b32_e32 v0, 3, v8
	v_lshl_add_u64 v[194:195], s[36:37], 0, v[16:17]
	s_lshl_b64 s[36:37], s[42:43], 1
	s_add_u32 s36, s18, s36
	v_and_b32_e32 v0, 56, v0
	global_load_dwordx4 v[66:69], v[4:5], off nt
	global_load_dwordx4 v[70:73], v[4:5], off offset:64 nt
	global_load_dwordx4 v[74:77], v[4:5], off offset:128 nt
	global_load_dwordx4 v[78:81], v[4:5], off offset:192 nt
	s_addc_u32 s37, s19, s37
	v_lshlrev_b32_e32 v4, 1, v0
	v_mov_b32_e32 v5, v1
	v_lshrrev_b32_sdwa v3, v211, v8 dst_sel:DWORD dst_unused:UNUSED_PAD src0_sel:DWORD src1_sel:BYTE_0
	v_lshl_add_u64 v[18:19], s[36:37], 0, v[4:5]
	v_or_b32_e32 v0, s42, v3
	v_lshrrev_b32_sdwa v5, v212, v8 dst_sel:DWORD dst_unused:UNUSED_PAD src0_sel:DWORD src1_sel:BYTE_0
	v_mad_i64_i32 v[10:11], s[36:37], v0, s59, v[194:195]
	v_mul_u32_u24_e32 v0, 0x2040, v5
	v_lshlrev_b32_e32 v0, 1, v0
	s_movk_i32 s24, 0x100
	v_lshl_add_u64 v[12:13], v[18:19], 0, v[0:1]
	global_load_dwordx4 v[86:89], v[10:11], off offset:2048
	global_load_dwordx4 v[90:93], v[12:13], off
	v_or_b32_sdwa v10, v8, s24 dst_sel:DWORD dst_unused:UNUSED_PAD src0_sel:BYTE_0 src1_sel:DWORD
	v_lshrrev_b32_e32 v9, 4, v10
	v_or_b32_e32 v11, s42, v9
	v_mad_i64_i32 v[12:13], s[36:37], v11, s59, v[194:195]
	v_lshrrev_b32_e32 v11, 3, v10
	v_mul_u32_u24_e32 v10, 0x2040, v11
	v_lshlrev_b32_e32 v196, 1, v10
	v_mov_b32_e32 v197, v1
	s_movk_i32 s24, 0x200
	v_lshl_add_u64 v[20:21], v[18:19], 0, v[196:197]
	global_load_dwordx4 v[94:97], v[12:13], off offset:2048
	global_load_dwordx4 v[98:101], v[20:21], off
	v_or_b32_sdwa v12, v8, s24 dst_sel:DWORD dst_unused:UNUSED_PAD src0_sel:BYTE_0 src1_sel:DWORD
	v_lshrrev_b32_e32 v10, 4, v12
	v_or_b32_e32 v13, s42, v10
	v_lshrrev_b32_e32 v12, 3, v12
	v_mad_i64_i32 v[20:21], s[36:37], v13, s59, v[194:195]
	v_mul_u32_u24_e32 v13, 0x2040, v12
	s_movk_i32 s24, 0x300
	v_lshlrev_b32_e32 v198, 1, v13
	v_or_b32_sdwa v13, v8, s24 dst_sel:DWORD dst_unused:UNUSED_PAD src0_sel:BYTE_0 src1_sel:DWORD
	v_lshrrev_b32_e32 v8, 4, v13
	v_mov_b32_e32 v199, v1
	v_or_b32_e32 v17, s42, v8
	v_lshrrev_b32_e32 v13, 3, v13
	v_lshl_add_u64 v[22:23], v[18:19], 0, v[198:199]
	global_load_dwordx4 v[118:121], v[20:21], off offset:2048
	global_load_dwordx4 v[122:125], v[22:23], off
	v_mad_i64_i32 v[20:21], s[36:37], v17, s59, v[194:195]
	v_mul_u32_u24_e32 v17, 0x2040, v13
	v_lshlrev_b32_e32 v200, 1, v17
	v_mov_b32_e32 v201, v1
	v_or_b32_e32 v190, 16, v192
	v_lshl_add_u64 v[18:19], v[18:19], 0, v[200:201]
	v_mad_i64_i32 v[14:15], s[36:37], v190, s59, v[14:15]
	global_load_dwordx4 v[130:133], v[20:21], off offset:2048
	global_load_dwordx4 v[134:137], v[18:19], off
	global_load_dwordx4 v[102:105], v[14:15], off nt
	global_load_dwordx4 v[106:109], v[14:15], off offset:64 nt
	global_load_dwordx4 v[110:113], v[14:15], off offset:128 nt
	global_load_dwordx4 v[114:117], v[14:15], off offset:192 nt
	s_mul_i32 s22, s22, 0x11800
	s_add_i32 s24, s22, 0
	v_add_u32_e32 v191, s24, v16
	v_and_b32_e32 v14, 0x70, v24
	s_movk_i32 s7, 0x110
	v_add_u32_e32 v193, s24, v14
	v_mad_u32_u24 v14, v3, s7, v191
	s_movk_i32 s6, 0x90
	s_mov_b64 s[36:37], -1
	s_cmp_gt_i32 s39, -1
	v_lshlrev_b32_e32 v216, 2, v7
	s_waitcnt vmcnt(0)
	v_mul_f32_e32 v244, 0x3fb8aa3b, v244
	ds_write_b32 v245, v244
	v_mul_f32_e32 v246, 0x3fb8aa3b, v246
	v_mov_b32_e32 v247, s14
	ds_write_b32 v247, v246 offset:1024
	ds_write_b128 v14, v[86:89]
	v_mad_u32_u24 v14, v5, s6, v193
	ds_write_b128 v14, v[90:93] offset:34816
	v_mad_u32_u24 v14, v9, s7, v191
	ds_write_b128 v14, v[94:97]
	v_mad_u32_u24 v14, v11, s6, v193
	ds_write_b128 v14, v[98:101] offset:34816
	v_mad_u32_u24 v14, v10, s7, v191
	ds_write_b128 v14, v[118:121]
	v_mad_u32_u24 v14, v12, s6, v193
	ds_write_b128 v14, v[122:125] offset:34816
	v_mad_u32_u24 v14, v8, s7, v191
	ds_write_b128 v14, v[130:133]
	v_mad_u32_u24 v14, v13, s6, v193
	ds_write_b128 v14, v[134:137] offset:34816
	s_waitcnt lgkmcnt(0)
	s_barrier
	s_cbranch_scc1 .LBB0_379
	v_lshlrev_b32_e32 v138, 2, v7
	s_mov_b64 s[36:37], 0
